# quant_gu: the first 11 of 32 k-blocks quantised by a second side job inside the P4 out-proj K-loop (one row per iteration, dword stores), P5 loop starts behind them
# baseline (speedup 1.0000x reference)
.LBB0_1002:
	s_lshl_b32 s47, s6, 6
	s_lshl_b32 s11, s6, 13
	s_lshl_b32 s6, s7, 5
	s_and_b32 s48, s6, 0x60
	s_mov_b64 s[6:7], 0x80
	s_add_i32 m0, s43, 0x18000
	v_lshl_add_u64 v[8:9], v[8:9], 0, s[6:7]
	s_lshl_b32 s12, s48, 7
	s_waitcnt vmcnt(2)
	s_barrier
	global_load_lds_dwordx4 v[8:9], off
	v_lshl_add_u64 v[2:3], v[2:3], 0, s[6:7]
	s_add_i32 m0, s43, 0x1a000
	s_add_i32 s49, s43, 0x8000
	s_add_i32 s50, s43, 0xa000
	global_load_lds_dwordx4 v[2:3], off
	v_lshl_add_u64 v[0:1], v[0:1], 0, s[6:7]
	s_mov_b32 m0, s49
	s_add_u32 s8, s28, 0x100080
	global_load_lds_dwordx4 v[0:1], off
	v_lshl_add_u64 v[0:1], v[6:7], 0, s[6:7]
	s_mov_b32 m0, s50
	s_addc_u32 s9, s29, 0
	global_load_lds_dwordx4 v[0:1], off
	s_add_i32 m0, s43, 0x1c000
	v_lshl_add_u64 v[0:1], s[8:9], 0, v[138:139]
	global_load_lds_dwordx4 v[0:1], off
	v_lshl_add_u64 v[0:1], s[8:9], 0, v[142:143]
	s_add_i32 m0, s43, 0x1e000
	v_bfe_u32 v162, v5, 4, 2
	global_load_lds_dwordx4 v[0:1], off
	v_and_b32_e32 v161, 15, v5
	v_lshlrev_b32_e32 v0, 4, v162
	v_lshlrev_b32_e32 v1, 2, v5
	v_lshl_or_b32 v0, v161, 6, v0
	v_and_b32_e32 v1, 32, v1
	v_bitop3_b32 v8, v0, s11, v1 bitop3:0xde
	v_bitop3_b32 v163, v0, s12, v1 bitop3:0xde
	v_lshlrev_b32_e32 v0, 2, v158
	v_ashrrev_i32_e32 v1, 31, v0
	v_lshl_add_u64 v[2:3], v[0:1], 2, s[96:97]
	v_lshlrev_b32_e32 v1, 16, v10
	s_mov_b64 s[12:13], 0xc0000
	v_and_b32_e32 v1, 0xfffe0000, v1
	v_lshl_add_u64 v[144:145], v[2:3], 0, s[12:13]
	v_lshl_add_u32 v1, v11, 13, v1
	v_and_b32_e32 v2, 1, v10
	v_lshl_or_b32 v1, v2, 6, v1
	v_lshl_add_u32 v146, v12, 1, v1
	v_lshlrev_b32_e32 v1, 16, v13
	v_and_b32_e32 v1, 0xfffe0000, v1
	s_cmpk_lt_u32 s10, 0x100
	v_lshl_add_u32 v1, v14, 13, v1
	v_and_b32_e32 v2, 1, v13
	s_waitcnt vmcnt(6)
	s_cselect_b64 s[10:11], -1, 0
	s_ashr_i32 s51, s47, 31
	v_and_b32_e32 v0, 0x7c, v0
	v_lshl_or_b32 v1, v2, 6, v1
	v_mov_b32_e32 v5, v4
	s_add_u32 s14, s96, 0x80000
	v_lshl_add_u32 v148, v15, 1, v1
	v_mov_b32_e32 v6, v4
	v_mov_b32_e32 v7, v4
	v_lshlrev_b32_e32 v150, 2, v0
	v_mov_b64_e32 v[0:1], v[4:5]
	s_mov_b32 s9, 0
	s_addc_u32 s15, s97, 0
	v_lshlrev_b32_e32 v164, 3, v158
	v_mov_b32_e32 v147, v4
	v_mov_b32_e32 v149, v4
	v_mov_b32_e32 v160, s16
	v_mov_b32_e32 v165, s38
	s_movk_i32 s52, 0x1000
	s_add_i32 s53, 0, 0x10000
	s_add_i32 s54, 0, 0x14000
	v_add_u32_e32 v166, 0, v8
	s_mov_b64 s[16:17], 0x40000
	v_mov_b64_e32 v[2:3], v[6:7]
	s_mov_b32 s55, 0
	s_barrier
	v_mbcnt_lo_u32_b32 v137, -1, 0
	v_mbcnt_hi_u32_b32 v137, -1, v137
	v_and_b32_e32 v139, 7, v137
	v_lshrrev_b32_e32 v137, 3, v137
	v_mul_u32_u24_e32 v137, 0xac000, v137
	v_lshl_add_u32 v137, v139, 4, v137
	v_mov_b32_e32 v139, 0
	v_mov_b32_e32 v141, 0
	v_mov_b32_e32 v143, 0
	v_mov_b32_e32 v147, 0
	v_cvt_f32_u32_e32 v244, s94
	v_rcp_iflag_f32_e32 v244, v244
	s_nop 1
	v_mul_f32_e32 v244, 0x4f7ffffe, v244
	v_cvt_u32_f32_e32 v244, v244
	s_nop 1
	v_readfirstlane_b32 s75, v244
	s_sub_i32 s76, 0, s94
	s_mul_i32 s76, s76, s75
	s_mul_hi_u32 s76, s75, s76
	s_add_i32 s75, s75, s76
	s_mov_b32 s77, 0x1d90
	s_mul_hi_u32 s76, s77, s75
	s_mul_i32 s98, s76, s94
	s_sub_i32 s77, s77, s98
	s_add_i32 s98, s76, 1
	s_sub_i32 s99, s77, s94
	s_cmp_ge_u32 s77, s94
	s_cselect_b32 s76, s98, s76
	s_cselect_b32 s77, s99, s77
	s_add_i32 s98, s76, 1
	s_sub_i32 s99, s77, s94
	s_cmp_ge_u32 s77, s94
	s_cselect_b32 s76, s98, s76
	s_cselect_b32 s77, s99, s77
	s_mul_i32 s84, s86, s76
	s_min_u32 s98, s86, s77
	s_add_u32 s84, s84, s98
	s_cmp_lt_u32 s86, s77
	s_addc_u32 s87, s84, s76
	s_min_u32 s84, s84, 0x1d90
	s_min_u32 s87, s87, 0x1d90
	s_lshl_b32 s84, s84, 4
	s_lshl_b32 s87, s87, 4
	s_mov_b32 s89, 0
	s_mov_b32 s32, 0
	s_cmp_lt_u32 s84, s87
	s_cbranch_scc0 .Lg_nbok_i
	s_lshr_b32 s76, s84, 4
	s_mul_i32 s77, s76, 5958
	s_lshr_b32 s77, s77, 16
	s_branch .Lg_newnb_i
.Lg_newnb_i:
	s_add_u32 s89, s77, 1
	s_mul_i32 s89, s89, 0xb0
	s_lshl_b32 s75, s77, 7
	s_add_u32 s75, s75, 0x80000
	v_and_b32_e32 v244, 0x70, v137
	v_add_u32_e32 v244, s75, v244
	global_load_dwordx4 v[244:247], v244, s[96:97]
	s_mov_b32 s75, 0x42fe0000
	s_waitcnt vmcnt(0)
	v_div_scale_f32 v248, vcc, v244, v244, s75
	v_rcp_f32_e32 v249, v248
	s_nop 1
	v_fma_f32 v255, -v248, v249, 1.0
	v_fmac_f32_e32 v249, v255, v249
	v_div_scale_f32 v255, vcc, s75, v244, s75
	v_mul_f32_e32 v149, v255, v249
	v_fma_f32 v139, -v248, v149, v255
	v_fmac_f32_e32 v149, v139, v249
	v_fma_f32 v248, -v248, v149, v255
	s_nop 4
	v_div_fmas_f32 v248, v248, v249, v149
	v_div_fixup_f32 v248, v248, v244, s75
	v_cmp_lt_f32_e32 vcc, 0, v244
	s_nop 1
	v_cndmask_b32_e32 v139, 0, v248, vcc
	v_div_scale_f32 v248, vcc, v245, v245, s75
	v_rcp_f32_e32 v249, v248
	s_nop 1
	v_fma_f32 v255, -v248, v249, 1.0
	v_fmac_f32_e32 v249, v255, v249
	v_div_scale_f32 v255, vcc, s75, v245, s75
	v_mul_f32_e32 v149, v255, v249
	v_fma_f32 v141, -v248, v149, v255
	v_fmac_f32_e32 v149, v141, v249
	v_fma_f32 v248, -v248, v149, v255
	s_nop 4
	v_div_fmas_f32 v248, v248, v249, v149
	v_div_fixup_f32 v248, v248, v245, s75
	v_cmp_lt_f32_e32 vcc, 0, v245
	s_nop 1
	v_cndmask_b32_e32 v141, 0, v248, vcc
	v_div_scale_f32 v248, vcc, v246, v246, s75
	v_rcp_f32_e32 v249, v248
	s_nop 1
	v_fma_f32 v255, -v248, v249, 1.0
	v_fmac_f32_e32 v249, v255, v249
	v_div_scale_f32 v255, vcc, s75, v246, s75
	v_mul_f32_e32 v149, v255, v249
	v_fma_f32 v143, -v248, v149, v255
	v_fmac_f32_e32 v149, v143, v249
	v_fma_f32 v248, -v248, v149, v255
	s_nop 4
	v_div_fmas_f32 v248, v248, v249, v149
	v_div_fixup_f32 v248, v248, v246, s75
	v_cmp_lt_f32_e32 vcc, 0, v246
	s_nop 1
	v_cndmask_b32_e32 v143, 0, v248, vcc
	v_div_scale_f32 v248, vcc, v247, v247, s75
	v_rcp_f32_e32 v249, v248
	s_nop 1
	v_fma_f32 v255, -v248, v249, 1.0
	v_fmac_f32_e32 v249, v255, v249
	v_div_scale_f32 v255, vcc, s75, v247, s75
	v_mul_f32_e32 v149, v255, v249
	v_fma_f32 v147, -v248, v149, v255
	v_fmac_f32_e32 v149, v147, v249
	v_fma_f32 v248, -v248, v149, v255
	s_nop 4
	v_div_fmas_f32 v248, v248, v249, v149
	v_div_fixup_f32 v248, v248, v247, s75
	v_cmp_lt_f32_e32 vcc, 0, v247
	s_nop 1
	v_cndmask_b32_e32 v147, 0, v248, vcc
	s_branch .Lg_nbok_i
.Lg_nbok_i:
.LBB0_1003:
	s_add_i32 s55, s55, 1
	v_sub_co_u32_e64 v5, s[20:21], s55, v165
	s_nop 0
	v_readfirstlane_b32 s8, v5
	s_and_b64 vcc, exec, s[20:21]
	s_mov_b32 s22, s55
	s_cbranch_vccnz .LBB0_1006
	s_cmp_lt_i32 s8, s39
	s_cselect_b64 s[20:21], -1, 0
	s_cmp_ge_i32 s8, s39
	s_cbranch_scc0 .LBB0_1047
	s_sub_i32 s20, s8, s39
	s_add_i32 s22, s20, s38
	s_cmp_lt_u32 s22, s37
	s_cselect_b64 s[20:21], -1, 0

.Lp4_body:
	s_add_i32 s8, s71, 2
	s_add_u32 s28, s26, 0xfff00080
	s_addc_u32 s29, s27, -1
	s_cmp_eq_u32 s68, s71
	s_cselect_b32 s31, s64, s29
	s_cselect_b32 s30, s65, s28
	s_cselect_b32 s29, s66, s70
	s_cselect_b32 s28, s67, s69
	v_add_u32_e32 v5, s53, v163
	ds_read_b128 v[172:175], v5
	ds_read_b128 v[176:179], v5 offset:1024
	ds_read_b128 v[180:183], v5 offset:2048
	ds_read_b128 v[184:187], v5 offset:3072
	v_add_u32_e32 v5, s54, v163
	ds_read_b128 v[188:191], v5
	ds_read_b128 v[192:195], v5 offset:1024
	ds_read_b128 v[196:199], v5 offset:2048
	ds_read_b128 v[200:203], v5 offset:3072
	s_add_i32 m0, s43, 0xc000
	ds_read_b128 v[204:207], v166
	ds_read_b128 v[208:211], v166 offset:1024
	ds_read_b128 v[212:215], v166 offset:2048
	ds_read_b128 v[216:219], v166 offset:3072
	ds_read_b128 v[220:223], v166 offset:4096
	ds_read_b128 v[224:227], v166 offset:5120
	ds_read_b128 v[236:239], v166 offset:6144
	ds_read_b128 v[240:243], v166 offset:7168
	global_load_lds_dwordx4 v146, s[26:27]
	s_add_i32 m0, s43, 0xe000
	s_nop 0
	global_load_lds_dwordx4 v148, s[26:27]
	s_bitcmp1_b32 s32, 31
	s_cbranch_scc0 .Lg_nost_p
	s_sub_u32 s75, s84, 4
	s_bfe_u32 s75, s75, 0x20002
	s_lshl_b32 s75, s75, 2
	s_add_u32 s76, s98, s75
	s_addc_u32 s77, s99, 0
	v_mbcnt_lo_u32_b32 v244, -1, 0
	v_mbcnt_hi_u32_b32 v244, -1, v244
	v_and_b32_e32 v245, 7, v244
	v_lshrrev_b32_e32 v244, 3, v244
	v_lshlrev_b32_e32 v244, 4, v244
	v_lshl_add_u32 v244, v245, 14, v244
	global_store_dword v244, v248, s[76:77]
	s_add_u32 s76, s76, 0x1000
	s_addc_u32 s77, s77, 0
	global_store_dword v244, v249, s[76:77]
	s_add_u32 s76, s76, 0x1000
	s_addc_u32 s77, s77, 0
	global_store_dword v244, v255, s[76:77]
	s_add_u32 s76, s76, 0x1000
	s_addc_u32 s77, s77, 0
	global_store_dword v244, v149, s[76:77]
	s_mov_b32 s32, 4
	s_branch .Lg_a_p

.Lg_a_p:
	s_cmp_lt_u32 s84, s87
	s_cbranch_scc0 .Lg_w_p
	s_and_b32 s75, s84, 15
	s_cbranch_scc0 .Lg_newitem_p
.Lg_ld_p:
	global_load_dwordx4 v[244:247], v137, s[100:101] nt
	s_add_u32 s100, s100, 0xac00
	s_addc_u32 s101, s101, 0
	s_or_b32 s32, s32, 1
	s_and_b32 s75, s84, 3
	s_add_u32 s84, s84, 1
	s_cmp_eq_u32 s75, 3
	s_cbranch_scc0 .Lg_w_p
	s_bitset1_b32 s32, 31
.Lg_w_p:
	s_and_b32 s75, s32, 7
	s_cbranch_scc1 .LgW1_p_nz
	s_waitcnt vmcnt(8)
	s_branch .LgW1_p_x
.LgW1_p_nz:
	s_cmp_eq_u32 s75, 1
	s_cbranch_scc1 .LgW1_p_1
	s_cmp_eq_u32 s75, 4
	s_cbranch_scc1 .LgW1_p_4
	s_waitcnt vmcnt(13)
	s_branch .LgW1_p_x
.LgW1_p_1:
	s_waitcnt vmcnt(9)
	s_branch .LgW1_p_x
.LgW1_p_4:
	s_waitcnt vmcnt(12)
.LgW1_p_x:
	s_waitcnt lgkmcnt(0)
	s_barrier
	s_setprio 1
	s_waitcnt lgkmcnt(0)
	v_mfma_f32_16x16x32_bf16 v[132:135], v[172:175], v[204:207], v[132:135]
	v_mfma_f32_16x16x32_bf16 v[128:131], v[180:183], v[204:207], v[128:131]
	v_mfma_f32_16x16x32_bf16 v[116:119], v[172:175], v[212:215], v[116:119]
	v_mfma_f32_16x16x32_bf16 v[112:115], v[180:183], v[212:215], v[112:115]
	v_mfma_f32_16x16x32_bf16 v[100:103], v[172:175], v[220:223], v[100:103]
	v_mfma_f32_16x16x32_bf16 v[96:99], v[180:183], v[220:223], v[96:99]
	v_mfma_f32_16x16x32_bf16 v[84:87], v[172:175], v[236:239], v[84:87]
	v_mfma_f32_16x16x32_bf16 v[80:83], v[180:183], v[236:239], v[80:83]
	v_mfma_f32_16x16x32_bf16 v[132:135], v[176:179], v[208:211], v[132:135]
	v_mfma_f32_16x16x32_bf16 v[128:131], v[184:187], v[208:211], v[128:131]
	v_mfma_f32_16x16x32_bf16 v[116:119], v[176:179], v[216:219], v[116:119]
	v_mfma_f32_16x16x32_bf16 v[112:115], v[184:187], v[216:219], v[112:115]
	v_mfma_f32_16x16x32_bf16 v[100:103], v[176:179], v[224:227], v[100:103]
	v_mfma_f32_16x16x32_bf16 v[96:99], v[184:187], v[224:227], v[96:99]
	v_mfma_f32_16x16x32_bf16 v[84:87], v[176:179], v[240:243], v[84:87]
	v_mfma_f32_16x16x32_bf16 v[80:83], v[184:187], v[240:243], v[80:83]
	s_setprio 0
	s_setprio 1
	v_mfma_f32_16x16x32_bf16 v[124:127], v[188:191], v[204:207], v[124:127]
	v_mfma_f32_16x16x32_bf16 v[120:123], v[196:199], v[204:207], v[120:123]
	v_mfma_f32_16x16x32_bf16 v[108:111], v[188:191], v[212:215], v[108:111]
	v_mfma_f32_16x16x32_bf16 v[104:107], v[196:199], v[212:215], v[104:107]
	v_mfma_f32_16x16x32_bf16 v[92:95], v[188:191], v[220:223], v[92:95]
	v_mfma_f32_16x16x32_bf16 v[88:91], v[196:199], v[220:223], v[88:91]
	v_mfma_f32_16x16x32_bf16 v[76:79], v[188:191], v[236:239], v[76:79]
	v_mfma_f32_16x16x32_bf16 v[72:75], v[196:199], v[236:239], v[72:75]
	v_mfma_f32_16x16x32_bf16 v[124:127], v[192:195], v[208:211], v[124:127]
	v_mfma_f32_16x16x32_bf16 v[120:123], v[200:203], v[208:211], v[120:123]
	v_mfma_f32_16x16x32_bf16 v[108:111], v[192:195], v[216:219], v[108:111]
	v_mfma_f32_16x16x32_bf16 v[104:107], v[200:203], v[216:219], v[104:107]
	v_mfma_f32_16x16x32_bf16 v[92:95], v[192:195], v[224:227], v[92:95]
	v_mfma_f32_16x16x32_bf16 v[88:91], v[200:203], v[224:227], v[88:91]
	v_mfma_f32_16x16x32_bf16 v[76:79], v[192:195], v[240:243], v[76:79]
	v_mfma_f32_16x16x32_bf16 v[72:75], v[200:203], v[240:243], v[72:75]
	s_setprio 0
	s_barrier
	s_add_i32 s71, s53, s40
	s_mov_b32 m0, s71
	ds_read_b128 v[204:207], v166 offset:16384
	ds_read_b128 v[208:211], v166 offset:17408
	ds_read_b128 v[212:215], v166 offset:18432
	ds_read_b128 v[216:219], v166 offset:19456
	ds_read_b128 v[220:223], v166 offset:20480
	ds_read_b128 v[224:227], v166 offset:21504
	ds_read_b128 v[236:239], v166 offset:22528
	ds_read_b128 v[240:243], v166 offset:23552
	global_load_lds_dwordx4 v138, s[28:29]
	s_add_i32 m0, s71, 0x2000
	s_add_u32 s72, s28, 0x100000
	s_addc_u32 s73, s29, 0
	s_add_i32 s71, s54, s40
	global_load_lds_dwordx4 v142, s[28:29]
	s_mov_b32 m0, s71
	s_nop 0
	global_load_lds_dwordx4 v138, s[72:73]
	s_add_i32 m0, s71, 0x2000
	s_nop 0
	global_load_lds_dwordx4 v142, s[72:73]
	s_mov_b32 m0, s43
	s_nop 0
	global_load_lds_dwordx4 v136, s[30:31]
	s_mov_b32 m0, s44
	s_nop 0
	global_load_lds_dwordx4 v140, s[30:31]
	s_and_b32 s75, s32, 7
	s_cbranch_scc1 .LgW2_p_nz
	s_waitcnt vmcnt(8)
	s_branch .LgW2_p_x

.LgW2_p_x:
	s_waitcnt lgkmcnt(0)
	s_barrier
	s_setprio 1
	s_waitcnt lgkmcnt(0)
	v_mfma_f32_16x16x32_bf16 v[68:71], v[172:175], v[204:207], v[68:71]
	v_mfma_f32_16x16x32_bf16 v[64:67], v[180:183], v[204:207], v[64:67]
	v_mfma_f32_16x16x32_bf16 v[52:55], v[172:175], v[212:215], v[52:55]
	v_mfma_f32_16x16x32_bf16 v[48:51], v[180:183], v[212:215], v[48:51]
	v_mfma_f32_16x16x32_bf16 v[36:39], v[172:175], v[220:223], v[36:39]
	v_mfma_f32_16x16x32_bf16 v[32:35], v[180:183], v[220:223], v[32:35]
	v_mfma_f32_16x16x32_bf16 v[20:23], v[172:175], v[236:239], v[20:23]
	v_mfma_f32_16x16x32_bf16 v[16:19], v[180:183], v[236:239], v[16:19]
	v_mfma_f32_16x16x32_bf16 v[68:71], v[176:179], v[208:211], v[68:71]
	v_mfma_f32_16x16x32_bf16 v[64:67], v[184:187], v[208:211], v[64:67]
	v_mfma_f32_16x16x32_bf16 v[52:55], v[176:179], v[216:219], v[52:55]
	v_mfma_f32_16x16x32_bf16 v[48:51], v[184:187], v[216:219], v[48:51]
	v_mfma_f32_16x16x32_bf16 v[36:39], v[176:179], v[224:227], v[36:39]
	v_mfma_f32_16x16x32_bf16 v[32:35], v[184:187], v[224:227], v[32:35]
	v_mfma_f32_16x16x32_bf16 v[20:23], v[176:179], v[240:243], v[20:23]
	v_mfma_f32_16x16x32_bf16 v[16:19], v[184:187], v[240:243], v[16:19]
	s_setprio 0
	s_setprio 1
	v_mfma_f32_16x16x32_bf16 v[60:63], v[188:191], v[204:207], v[60:63]
	v_mfma_f32_16x16x32_bf16 v[56:59], v[196:199], v[204:207], v[56:59]
	v_mfma_f32_16x16x32_bf16 v[44:47], v[188:191], v[212:215], v[44:47]
	v_mfma_f32_16x16x32_bf16 v[40:43], v[196:199], v[212:215], v[40:43]
	v_mfma_f32_16x16x32_bf16 v[28:31], v[188:191], v[220:223], v[28:31]
	v_mfma_f32_16x16x32_bf16 v[24:27], v[196:199], v[220:223], v[24:27]
	v_mfma_f32_16x16x32_bf16 v[12:15], v[188:191], v[236:239], v[12:15]
	v_mfma_f32_16x16x32_bf16 v[6:9], v[196:199], v[236:239], v[8:11]
	v_mfma_f32_16x16x32_bf16 v[60:63], v[192:195], v[208:211], v[60:63]
	v_mfma_f32_16x16x32_bf16 v[56:59], v[200:203], v[208:211], v[56:59]
	v_mfma_f32_16x16x32_bf16 v[44:47], v[192:195], v[216:219], v[44:47]
	v_mfma_f32_16x16x32_bf16 v[40:43], v[200:203], v[216:219], v[40:43]
	v_mfma_f32_16x16x32_bf16 v[28:31], v[192:195], v[224:227], v[28:31]
	v_mfma_f32_16x16x32_bf16 v[24:27], v[200:203], v[224:227], v[24:27]
	v_mfma_f32_16x16x32_bf16 v[12:15], v[192:195], v[240:243], v[12:15]
	v_mfma_f32_16x16x32_bf16 v[6:9], v[200:203], v[240:243], v[6:9]
	s_setprio 0
	s_barrier
	s_add_i32 s71, 0, 0x18000
	v_add_u32_e32 v5, s71, v163
	s_add_i32 s72, 0, 0x1c000
	ds_read_b128 v[172:175], v5
	ds_read_b128 v[176:179], v5 offset:1024
	ds_read_b128 v[180:183], v5 offset:2048
	ds_read_b128 v[184:187], v5 offset:3072
	v_add_u32_e32 v5, s72, v163
	ds_read_b128 v[188:191], v5
	ds_read_b128 v[192:195], v5 offset:1024
	ds_read_b128 v[196:199], v5 offset:2048
	ds_read_b128 v[200:203], v5 offset:3072
	s_add_u32 s30, s30, 0x100000
	s_addc_u32 s31, s31, 0
	s_mov_b32 m0, s45
	ds_read_b128 v[204:207], v166 offset:32768
	ds_read_b128 v[208:211], v166 offset:33792
	ds_read_b128 v[212:215], v166 offset:34816
	ds_read_b128 v[216:219], v166 offset:35840
	ds_read_b128 v[220:223], v166 offset:36864
	ds_read_b128 v[224:227], v166 offset:37888
	ds_read_b128 v[236:239], v166 offset:38912
	ds_read_b128 v[240:243], v166 offset:39936
	global_load_lds_dwordx4 v136, s[30:31]
	s_mov_b32 m0, s46
	s_nop 0
	global_load_lds_dwordx4 v140, s[30:31]
	s_and_b32 s75, s32, 7
	s_cbranch_scc1 .LgW3_p_nz
	s_waitcnt vmcnt(8)
	s_branch .LgW3_p_x

.LgW3_p_x:
	s_waitcnt lgkmcnt(0)
	s_barrier
	s_setprio 1
	s_waitcnt lgkmcnt(0)
	v_mfma_f32_16x16x32_bf16 v[132:135], v[172:175], v[204:207], v[132:135]
	v_mfma_f32_16x16x32_bf16 v[128:131], v[180:183], v[204:207], v[128:131]
	v_mfma_f32_16x16x32_bf16 v[116:119], v[172:175], v[212:215], v[116:119]
	v_mfma_f32_16x16x32_bf16 v[112:115], v[180:183], v[212:215], v[112:115]
	v_mfma_f32_16x16x32_bf16 v[100:103], v[172:175], v[220:223], v[100:103]
	v_mfma_f32_16x16x32_bf16 v[96:99], v[180:183], v[220:223], v[96:99]
	v_mfma_f32_16x16x32_bf16 v[84:87], v[172:175], v[236:239], v[84:87]
	v_mfma_f32_16x16x32_bf16 v[80:83], v[180:183], v[236:239], v[80:83]
	v_mfma_f32_16x16x32_bf16 v[132:135], v[176:179], v[208:211], v[132:135]
	v_mfma_f32_16x16x32_bf16 v[128:131], v[184:187], v[208:211], v[128:131]
	v_mfma_f32_16x16x32_bf16 v[116:119], v[176:179], v[216:219], v[116:119]
	v_mfma_f32_16x16x32_bf16 v[112:115], v[184:187], v[216:219], v[112:115]
	v_mfma_f32_16x16x32_bf16 v[100:103], v[176:179], v[224:227], v[100:103]
	v_mfma_f32_16x16x32_bf16 v[96:99], v[184:187], v[224:227], v[96:99]
	v_mfma_f32_16x16x32_bf16 v[84:87], v[176:179], v[240:243], v[84:87]
	v_mfma_f32_16x16x32_bf16 v[80:83], v[184:187], v[240:243], v[80:83]
	s_setprio 0
	s_setprio 1
	v_mfma_f32_16x16x32_bf16 v[124:127], v[188:191], v[204:207], v[124:127]
	v_mfma_f32_16x16x32_bf16 v[120:123], v[196:199], v[204:207], v[120:123]
	v_mfma_f32_16x16x32_bf16 v[108:111], v[188:191], v[212:215], v[108:111]
	v_mfma_f32_16x16x32_bf16 v[104:107], v[196:199], v[212:215], v[104:107]
	v_mfma_f32_16x16x32_bf16 v[92:95], v[188:191], v[220:223], v[92:95]
	v_mfma_f32_16x16x32_bf16 v[88:91], v[196:199], v[220:223], v[88:91]
	v_mfma_f32_16x16x32_bf16 v[76:79], v[188:191], v[236:239], v[76:79]
	v_mfma_f32_16x16x32_bf16 v[72:75], v[196:199], v[236:239], v[72:75]
	v_mfma_f32_16x16x32_bf16 v[124:127], v[192:195], v[208:211], v[124:127]
	v_mfma_f32_16x16x32_bf16 v[120:123], v[200:203], v[208:211], v[120:123]
	v_mfma_f32_16x16x32_bf16 v[108:111], v[192:195], v[216:219], v[108:111]
	v_mfma_f32_16x16x32_bf16 v[104:107], v[200:203], v[216:219], v[104:107]
	v_mfma_f32_16x16x32_bf16 v[92:95], v[192:195], v[224:227], v[92:95]
	v_mfma_f32_16x16x32_bf16 v[88:91], v[200:203], v[224:227], v[88:91]
	v_mfma_f32_16x16x32_bf16 v[76:79], v[192:195], v[240:243], v[76:79]
	v_mfma_f32_16x16x32_bf16 v[72:75], v[200:203], v[240:243], v[72:75]
	s_setprio 0
	s_barrier
	s_add_u32 s74, s28, s6
	s_addc_u32 s75, s29, s7
	s_add_u32 s76, s30, s6
	s_addc_u32 s77, s31, s7
	s_sub_u32 s76, s76, 0x100000
	s_subb_u32 s77, s77, 0
	s_add_i32 s30, s71, s40
	s_mov_b32 m0, s30
	ds_read_b128 v[152:155], v166 offset:49152
	ds_read_b128 v[168:171], v166 offset:50176
	ds_read_b128 v[204:207], v166 offset:51200
	ds_read_b128 v[208:211], v166 offset:52224
	ds_read_b128 v[212:215], v166 offset:53248
	ds_read_b128 v[216:219], v166 offset:54272
	ds_read_b128 v[220:223], v166 offset:55296
	ds_read_b128 v[224:227], v166 offset:56320
	global_load_lds_dwordx4 v138, s[74:75]
	s_add_i32 m0, s30, 0x2000
	s_add_u32 s28, s28, 0x100080
	s_addc_u32 s29, s29, 0
	s_add_i32 s30, s72, s40
	global_load_lds_dwordx4 v142, s[74:75]
	s_mov_b32 m0, s30
	s_nop 0
	global_load_lds_dwordx4 v138, s[28:29]
	s_add_i32 m0, s30, 0x2000
	s_nop 0
	global_load_lds_dwordx4 v142, s[28:29]
	s_mov_b32 m0, s49
	s_nop 0
	global_load_lds_dwordx4 v136, s[76:77]
	s_mov_b32 m0, s50
	s_nop 0
	global_load_lds_dwordx4 v140, s[76:77]
	s_waitcnt vmcnt(8)
	s_waitcnt lgkmcnt(0)
	s_barrier
	s_setprio 1
	s_waitcnt lgkmcnt(0)
	v_mfma_f32_16x16x32_bf16 v[68:71], v[172:175], v[152:155], v[68:71]
	v_mfma_f32_16x16x32_bf16 v[64:67], v[180:183], v[152:155], v[64:67]
	v_mfma_f32_16x16x32_bf16 v[52:55], v[172:175], v[204:207], v[52:55]
	v_mfma_f32_16x16x32_bf16 v[48:51], v[180:183], v[204:207], v[48:51]
	v_fmaak_f32 v244, v244, v139, 0x4b400000
	v_mfma_f32_16x16x32_bf16 v[36:39], v[172:175], v[212:215], v[36:39]
	v_mfma_f32_16x16x32_bf16 v[32:35], v[180:183], v[212:215], v[32:35]
	v_mfma_f32_16x16x32_bf16 v[20:23], v[172:175], v[220:223], v[20:23]
	v_mfma_f32_16x16x32_bf16 v[16:19], v[180:183], v[220:223], v[16:19]
	v_fmaak_f32 v245, v245, v141, 0x4b400000
	v_mfma_f32_16x16x32_bf16 v[68:71], v[176:179], v[168:171], v[68:71]
	v_mfma_f32_16x16x32_bf16 v[64:67], v[184:187], v[168:171], v[64:67]
	v_mfma_f32_16x16x32_bf16 v[52:55], v[176:179], v[208:211], v[52:55]
	v_mfma_f32_16x16x32_bf16 v[48:51], v[184:187], v[208:211], v[48:51]
	v_fmaak_f32 v246, v246, v143, 0x4b400000
	v_mfma_f32_16x16x32_bf16 v[36:39], v[176:179], v[216:219], v[36:39]
	v_mfma_f32_16x16x32_bf16 v[32:35], v[184:187], v[216:219], v[32:35]
	v_mfma_f32_16x16x32_bf16 v[20:23], v[176:179], v[224:227], v[20:23]
	v_mfma_f32_16x16x32_bf16 v[16:19], v[184:187], v[224:227], v[16:19]
	v_fmaak_f32 v247, v247, v147, 0x4b400000
	s_setprio 0
	s_setprio 1
	v_mfma_f32_16x16x32_bf16 v[60:63], v[188:191], v[152:155], v[60:63]
	v_mfma_f32_16x16x32_bf16 v[56:59], v[196:199], v[152:155], v[56:59]
	v_mfma_f32_16x16x32_bf16 v[44:47], v[188:191], v[204:207], v[44:47]
	v_mfma_f32_16x16x32_bf16 v[40:43], v[196:199], v[204:207], v[40:43]
	v_alignbit_b32 v248, v244, v248, 8
	v_mfma_f32_16x16x32_bf16 v[28:31], v[188:191], v[212:215], v[28:31]
	v_mfma_f32_16x16x32_bf16 v[24:27], v[196:199], v[212:215], v[24:27]
	v_mfma_f32_16x16x32_bf16 v[10:13], v[188:191], v[220:223], v[12:15]
	v_mfma_f32_16x16x32_bf16 v[6:9], v[196:199], v[220:223], v[6:9]
	v_alignbit_b32 v249, v245, v249, 8
	v_mfma_f32_16x16x32_bf16 v[60:63], v[192:195], v[168:171], v[60:63]
	v_mfma_f32_16x16x32_bf16 v[56:59], v[200:203], v[168:171], v[56:59]
	v_mfma_f32_16x16x32_bf16 v[44:47], v[192:195], v[208:211], v[44:47]
	v_mfma_f32_16x16x32_bf16 v[40:43], v[200:203], v[208:211], v[40:43]
	v_alignbit_b32 v255, v246, v255, 8
	v_mfma_f32_16x16x32_bf16 v[28:31], v[192:195], v[216:219], v[28:31]
	v_mfma_f32_16x16x32_bf16 v[24:27], v[200:203], v[216:219], v[24:27]
	v_mfma_f32_16x16x32_bf16 v[12:15], v[192:195], v[224:227], v[10:13]
	v_mfma_f32_16x16x32_bf16 v[8:11], v[200:203], v[224:227], v[6:9]
	v_alignbit_b32 v149, v247, v149, 8
	s_setprio 0
	s_barrier
	s_add_u32 s26, s26, 0x100
	s_addc_u32 s27, s27, 0
	s_add_u32 s69, s69, 0x100
	s_addc_u32 s70, s70, 0
	s_cmp_ge_i32 s8, s63
	s_cbranch_scc0 .Lp4_top
	s_branch .Lp4_epi
.Lg_newitem_p:
	s_lshr_b32 s76, s84, 4
	s_mul_i32 s77, s76, 5958
	s_lshr_b32 s77, s77, 16
	s_cmp_lt_u32 s84, s89
	s_cbranch_scc0 .Lg_newnb_p
.Lg_nbok_p:
	s_mul_i32 s75, s77, 11
	s_sub_u32 s76, s76, s75
	s_lshl_b32 s76, s76, 7
	s_lshl_b32 s75, s77, 17
	s_add_u32 s75, s75, s76
	s_add_u32 s75, s75, 0x8300000
	s_add_u32 s98, s96, s75
	s_addc_u32 s99, s97, 0
	s_mul_i32 s76, s76, 0xac00
	s_lshr_b32 s75, s77, 3
	s_lshl_b32 s75, s75, 9
	s_add_u32 s76, s76, s75
	s_and_b32 s75, s77, 3
	s_lshl_b32 s75, s75, 7
	s_add_u32 s76, s76, s75
	s_bitcmp1_b32 s77, 2
	s_cbranch_scc1 .Lg_up_p
	s_load_dwordx2 s[100:101], s[0:1], 0x78
	s_branch .Lg_mat_p
.Lg_up_p:
	s_load_dwordx2 s[100:101], s[0:1], 0x80
.Lg_mat_p:
	s_waitcnt lgkmcnt(0)
	s_add_u32 s100, s100, s76
	s_addc_u32 s101, s101, 0
	s_branch .Lg_ld_p

.LBB0_1033:
	s_add_i32 s8, s71, 2
	s_add_u32 s28, s26, 0xfff00080
	s_addc_u32 s29, s27, -1
	s_cmp_eq_u32 s68, s71
	s_cselect_b32 s31, s64, s29
	s_cselect_b32 s30, s65, s28
	s_cselect_b32 s29, s66, s70
	s_cselect_b32 s28, s67, s69
	s_cmpk_lt_i32 s3, 0x56
	s_cselect_b32 s71, s52, 0x2b00
	s_mov_b32 s72, 0xac00
	s_cselect_b32 s74, s72, 0x4000
	s_sub_i32 s71, s71, s33
	v_min3_i32 v5, s71, v160, 2
	v_sub_u32_e32 v160, v160, v5
	v_readfirstlane_b32 s71, v5
	s_max_i32 s72, s71, 0
	s_add_i32 s72, s33, s72
	s_add_i32 s75, s72, -1
	s_min_i32 s72, s33, s75
	s_mul_hi_i32 s73, s74, s72
	s_mul_i32 s72, s74, s72
	s_add_u32 s72, s34, s72
	s_addc_u32 s73, s35, s73
	s_mul_hi_i32 s76, s74, s75
	s_mul_i32 s74, s74, s75
	s_add_u32 s74, s34, s74
	global_load_dwordx4 v[152:155], v159, s[72:73] nt
	s_addc_u32 s75, s35, s76
	global_load_dwordx4 v[168:171], v159, s[74:75] nt
	s_add_i32 s33, s71, s33
	v_add_u32_e32 v5, s53, v163
	ds_read_b128 v[172:175], v5
	ds_read_b128 v[176:179], v5 offset:1024
	ds_read_b128 v[180:183], v5 offset:2048
	ds_read_b128 v[184:187], v5 offset:3072
	v_add_u32_e32 v5, s54, v163
	ds_read_b128 v[188:191], v5
	ds_read_b128 v[192:195], v5 offset:1024
	ds_read_b128 v[196:199], v5 offset:2048
	ds_read_b128 v[200:203], v5 offset:3072
	s_add_i32 m0, s43, 0xc000
	ds_read_b128 v[204:207], v166
	ds_read_b128 v[208:211], v166 offset:1024
	ds_read_b128 v[212:215], v166 offset:2048
	ds_read_b128 v[216:219], v166 offset:3072
	ds_read_b128 v[220:223], v166 offset:4096
	ds_read_b128 v[224:227], v166 offset:5120
	ds_read_b128 v[236:239], v166 offset:6144
	ds_read_b128 v[240:243], v166 offset:7168
	global_load_lds_dwordx4 v146, s[26:27]
	s_add_i32 m0, s43, 0xe000
	s_nop 0
	global_load_lds_dwordx4 v148, s[26:27]
	s_bitcmp1_b32 s32, 31
	s_cbranch_scc0 .Lg_nost_s
	s_sub_u32 s75, s84, 4
	s_bfe_u32 s75, s75, 0x20002
	s_lshl_b32 s75, s75, 2
	s_add_u32 s76, s98, s75
	s_addc_u32 s77, s99, 0
	v_mbcnt_lo_u32_b32 v244, -1, 0
	v_mbcnt_hi_u32_b32 v244, -1, v244
	v_and_b32_e32 v245, 7, v244
	v_lshrrev_b32_e32 v244, 3, v244
	v_lshlrev_b32_e32 v244, 4, v244
	v_lshl_add_u32 v244, v245, 14, v244
	global_store_dword v244, v248, s[76:77]
	s_add_u32 s76, s76, 0x1000
	s_addc_u32 s77, s77, 0
	global_store_dword v244, v249, s[76:77]
	s_add_u32 s76, s76, 0x1000
	s_addc_u32 s77, s77, 0
	global_store_dword v244, v255, s[76:77]
	s_add_u32 s76, s76, 0x1000
	s_addc_u32 s77, s77, 0
	global_store_dword v244, v149, s[76:77]
	s_mov_b32 s32, 4
	s_branch .Lg_a_s

.Lg_w_s:
	s_and_b32 s75, s32, 7
	s_cbranch_scc1 .LgW1_s_nz
	s_waitcnt vmcnt(10)
	s_branch .LgW1_s_x
.LgW1_s_nz:
	s_cmp_eq_u32 s75, 1
	s_cbranch_scc1 .LgW1_s_1
	s_cmp_eq_u32 s75, 4
	s_cbranch_scc1 .LgW1_s_4
	s_waitcnt vmcnt(15)
	s_branch .LgW1_s_x
.LgW1_s_1:
	s_waitcnt vmcnt(11)
	s_branch .LgW1_s_x
.LgW1_s_4:
	s_waitcnt vmcnt(14)
.LgW1_s_x:
	s_waitcnt lgkmcnt(0)
	s_barrier
	s_setprio 1
	s_waitcnt lgkmcnt(0)
	v_mfma_f32_16x16x32_bf16 v[132:135], v[172:175], v[204:207], v[132:135]
	v_mfma_f32_16x16x32_bf16 v[128:131], v[180:183], v[204:207], v[128:131]
	v_mfma_f32_16x16x32_bf16 v[116:119], v[172:175], v[212:215], v[116:119]
	v_mfma_f32_16x16x32_bf16 v[112:115], v[180:183], v[212:215], v[112:115]
	v_mfma_f32_16x16x32_bf16 v[100:103], v[172:175], v[220:223], v[100:103]
	v_mfma_f32_16x16x32_bf16 v[96:99], v[180:183], v[220:223], v[96:99]
	v_mfma_f32_16x16x32_bf16 v[84:87], v[172:175], v[236:239], v[84:87]
	v_mfma_f32_16x16x32_bf16 v[80:83], v[180:183], v[236:239], v[80:83]
	v_mfma_f32_16x16x32_bf16 v[132:135], v[176:179], v[208:211], v[132:135]
	v_mfma_f32_16x16x32_bf16 v[128:131], v[184:187], v[208:211], v[128:131]
	v_mfma_f32_16x16x32_bf16 v[116:119], v[176:179], v[216:219], v[116:119]
	v_mfma_f32_16x16x32_bf16 v[112:115], v[184:187], v[216:219], v[112:115]
	v_mfma_f32_16x16x32_bf16 v[100:103], v[176:179], v[224:227], v[100:103]
	v_mfma_f32_16x16x32_bf16 v[96:99], v[184:187], v[224:227], v[96:99]
	v_mfma_f32_16x16x32_bf16 v[84:87], v[176:179], v[240:243], v[84:87]
	v_mfma_f32_16x16x32_bf16 v[80:83], v[184:187], v[240:243], v[80:83]
	s_setprio 0
	s_setprio 1
	v_mfma_f32_16x16x32_bf16 v[124:127], v[188:191], v[204:207], v[124:127]
	v_mfma_f32_16x16x32_bf16 v[120:123], v[196:199], v[204:207], v[120:123]
	v_mfma_f32_16x16x32_bf16 v[108:111], v[188:191], v[212:215], v[108:111]
	v_mfma_f32_16x16x32_bf16 v[104:107], v[196:199], v[212:215], v[104:107]
	v_mfma_f32_16x16x32_bf16 v[92:95], v[188:191], v[220:223], v[92:95]
	v_mfma_f32_16x16x32_bf16 v[88:91], v[196:199], v[220:223], v[88:91]
	v_mfma_f32_16x16x32_bf16 v[76:79], v[188:191], v[236:239], v[76:79]
	v_mfma_f32_16x16x32_bf16 v[72:75], v[196:199], v[236:239], v[72:75]
	v_mfma_f32_16x16x32_bf16 v[124:127], v[192:195], v[208:211], v[124:127]
	v_mfma_f32_16x16x32_bf16 v[120:123], v[200:203], v[208:211], v[120:123]
	v_mfma_f32_16x16x32_bf16 v[108:111], v[192:195], v[216:219], v[108:111]
	v_mfma_f32_16x16x32_bf16 v[104:107], v[200:203], v[216:219], v[104:107]
	v_mfma_f32_16x16x32_bf16 v[92:95], v[192:195], v[224:227], v[92:95]
	v_mfma_f32_16x16x32_bf16 v[88:91], v[200:203], v[224:227], v[88:91]
	v_mfma_f32_16x16x32_bf16 v[76:79], v[192:195], v[240:243], v[76:79]
	v_mfma_f32_16x16x32_bf16 v[72:75], v[200:203], v[240:243], v[72:75]
	s_setprio 0
	s_barrier
	s_add_i32 s71, s53, s40
	s_mov_b32 m0, s71
	ds_read_b128 v[204:207], v166 offset:16384
	ds_read_b128 v[208:211], v166 offset:17408
	ds_read_b128 v[212:215], v166 offset:18432
	ds_read_b128 v[216:219], v166 offset:19456
	ds_read_b128 v[220:223], v166 offset:20480
	ds_read_b128 v[224:227], v166 offset:21504
	ds_read_b128 v[236:239], v166 offset:22528
	ds_read_b128 v[240:243], v166 offset:23552
	global_load_lds_dwordx4 v138, s[28:29]
	s_add_i32 m0, s71, 0x2000
	s_add_u32 s72, s28, 0x100000
	s_addc_u32 s73, s29, 0
	s_add_i32 s71, s54, s40
	global_load_lds_dwordx4 v142, s[28:29]
	s_mov_b32 m0, s71
	s_nop 0
	global_load_lds_dwordx4 v138, s[72:73]
	s_add_i32 m0, s71, 0x2000
	s_nop 0
	global_load_lds_dwordx4 v142, s[72:73]
	s_mov_b32 m0, s43
	s_nop 0
	global_load_lds_dwordx4 v136, s[30:31]
	s_mov_b32 m0, s44
	s_nop 0
	global_load_lds_dwordx4 v140, s[30:31]
	s_and_b32 s75, s32, 7
	s_cbranch_scc1 .LgW2_s_nz
	s_waitcnt vmcnt(10)
	s_branch .LgW2_s_x

.LgW3_s_x:
	s_waitcnt lgkmcnt(0)
	s_barrier
	s_setprio 1
	s_waitcnt lgkmcnt(0)
	v_mfma_f32_16x16x32_bf16 v[132:135], v[172:175], v[204:207], v[132:135]
	v_mfma_f32_16x16x32_bf16 v[128:131], v[180:183], v[204:207], v[128:131]
	v_mfma_f32_16x16x32_bf16 v[116:119], v[172:175], v[212:215], v[116:119]
	v_mfma_f32_16x16x32_bf16 v[112:115], v[180:183], v[212:215], v[112:115]
	v_mfma_f32_16x16x32_bf16 v[100:103], v[172:175], v[220:223], v[100:103]
	v_max3_f32 v0, v0, |v152|, |v168|
	v_mfma_f32_16x16x32_bf16 v[96:99], v[180:183], v[220:223], v[96:99]
	v_max3_f32 v1, v1, |v153|, |v169|
	v_mfma_f32_16x16x32_bf16 v[84:87], v[172:175], v[236:239], v[84:87]
	v_max3_f32 v2, v2, |v154|, |v170|
	v_mfma_f32_16x16x32_bf16 v[80:83], v[180:183], v[236:239], v[80:83]
	v_max3_f32 v3, v3, |v155|, |v171|
	v_mfma_f32_16x16x32_bf16 v[132:135], v[176:179], v[208:211], v[132:135]
	v_mfma_f32_16x16x32_bf16 v[128:131], v[184:187], v[208:211], v[128:131]
	v_mfma_f32_16x16x32_bf16 v[116:119], v[176:179], v[216:219], v[116:119]
	v_mfma_f32_16x16x32_bf16 v[112:115], v[184:187], v[216:219], v[112:115]
	v_mfma_f32_16x16x32_bf16 v[100:103], v[176:179], v[224:227], v[100:103]
	v_mfma_f32_16x16x32_bf16 v[96:99], v[184:187], v[224:227], v[96:99]
	v_mfma_f32_16x16x32_bf16 v[84:87], v[176:179], v[240:243], v[84:87]
	v_mfma_f32_16x16x32_bf16 v[80:83], v[184:187], v[240:243], v[80:83]
	s_setprio 0
	s_setprio 1
	v_mfma_f32_16x16x32_bf16 v[124:127], v[188:191], v[204:207], v[124:127]
	v_mfma_f32_16x16x32_bf16 v[120:123], v[196:199], v[204:207], v[120:123]
	v_mfma_f32_16x16x32_bf16 v[108:111], v[188:191], v[212:215], v[108:111]
	v_mfma_f32_16x16x32_bf16 v[104:107], v[196:199], v[212:215], v[104:107]
	v_mfma_f32_16x16x32_bf16 v[92:95], v[188:191], v[220:223], v[92:95]
	v_mfma_f32_16x16x32_bf16 v[88:91], v[196:199], v[220:223], v[88:91]
	v_mfma_f32_16x16x32_bf16 v[76:79], v[188:191], v[236:239], v[76:79]
	v_mfma_f32_16x16x32_bf16 v[72:75], v[196:199], v[236:239], v[72:75]
	v_mfma_f32_16x16x32_bf16 v[124:127], v[192:195], v[208:211], v[124:127]
	v_mfma_f32_16x16x32_bf16 v[120:123], v[200:203], v[208:211], v[120:123]
	v_mfma_f32_16x16x32_bf16 v[108:111], v[192:195], v[216:219], v[108:111]
	v_mfma_f32_16x16x32_bf16 v[104:107], v[200:203], v[216:219], v[104:107]
	v_mfma_f32_16x16x32_bf16 v[92:95], v[192:195], v[224:227], v[92:95]
	v_mfma_f32_16x16x32_bf16 v[88:91], v[200:203], v[224:227], v[88:91]
	v_mfma_f32_16x16x32_bf16 v[76:79], v[192:195], v[240:243], v[76:79]
	v_mfma_f32_16x16x32_bf16 v[72:75], v[200:203], v[240:243], v[72:75]
	s_setprio 0
	s_barrier
	s_add_u32 s74, s28, s6
	s_addc_u32 s75, s29, s7
	s_add_u32 s76, s30, s6
	s_addc_u32 s77, s31, s7
	s_sub_u32 s76, s76, 0x100000
	s_subb_u32 s77, s77, 0
	s_add_i32 s30, s71, s40
	s_mov_b32 m0, s30
	ds_read_b128 v[152:155], v166 offset:49152
	ds_read_b128 v[168:171], v166 offset:50176
	ds_read_b128 v[204:207], v166 offset:51200
	ds_read_b128 v[208:211], v166 offset:52224
	ds_read_b128 v[212:215], v166 offset:53248
	ds_read_b128 v[216:219], v166 offset:54272
	ds_read_b128 v[220:223], v166 offset:55296
	ds_read_b128 v[224:227], v166 offset:56320
	global_load_lds_dwordx4 v138, s[74:75]
	s_add_i32 m0, s30, 0x2000
	s_add_u32 s28, s28, 0x100080
	s_addc_u32 s29, s29, 0
	s_add_i32 s30, s72, s40
	global_load_lds_dwordx4 v142, s[74:75]
	s_mov_b32 m0, s30
	s_nop 0
	global_load_lds_dwordx4 v138, s[28:29]
	s_add_i32 m0, s30, 0x2000
	s_nop 0
	global_load_lds_dwordx4 v142, s[28:29]
	s_mov_b32 m0, s49
	s_nop 0
	global_load_lds_dwordx4 v136, s[76:77]
	s_mov_b32 m0, s50
	s_nop 0
	global_load_lds_dwordx4 v140, s[76:77]
	s_waitcnt vmcnt(8)
	s_waitcnt lgkmcnt(0)
	s_barrier
	s_setprio 1
	s_waitcnt lgkmcnt(0)
	v_mfma_f32_16x16x32_bf16 v[68:71], v[172:175], v[152:155], v[68:71]
	v_mfma_f32_16x16x32_bf16 v[64:67], v[180:183], v[152:155], v[64:67]
	v_mfma_f32_16x16x32_bf16 v[52:55], v[172:175], v[204:207], v[52:55]
	v_mfma_f32_16x16x32_bf16 v[48:51], v[180:183], v[204:207], v[48:51]
	v_fmaak_f32 v244, v244, v139, 0x4b400000
	v_mfma_f32_16x16x32_bf16 v[36:39], v[172:175], v[212:215], v[36:39]
	v_mfma_f32_16x16x32_bf16 v[32:35], v[180:183], v[212:215], v[32:35]
	v_mfma_f32_16x16x32_bf16 v[20:23], v[172:175], v[220:223], v[20:23]
	v_mfma_f32_16x16x32_bf16 v[16:19], v[180:183], v[220:223], v[16:19]
	v_fmaak_f32 v245, v245, v141, 0x4b400000
	v_mfma_f32_16x16x32_bf16 v[68:71], v[176:179], v[168:171], v[68:71]
	v_mfma_f32_16x16x32_bf16 v[64:67], v[184:187], v[168:171], v[64:67]
	v_mfma_f32_16x16x32_bf16 v[52:55], v[176:179], v[208:211], v[52:55]
	v_mfma_f32_16x16x32_bf16 v[48:51], v[184:187], v[208:211], v[48:51]
	v_fmaak_f32 v246, v246, v143, 0x4b400000
	v_mfma_f32_16x16x32_bf16 v[36:39], v[176:179], v[216:219], v[36:39]
	v_mfma_f32_16x16x32_bf16 v[32:35], v[184:187], v[216:219], v[32:35]
	v_mfma_f32_16x16x32_bf16 v[20:23], v[176:179], v[224:227], v[20:23]
	v_mfma_f32_16x16x32_bf16 v[16:19], v[184:187], v[224:227], v[16:19]
	v_fmaak_f32 v247, v247, v147, 0x4b400000
	s_setprio 0
	s_setprio 1
	v_mfma_f32_16x16x32_bf16 v[60:63], v[188:191], v[152:155], v[60:63]
	v_mfma_f32_16x16x32_bf16 v[56:59], v[196:199], v[152:155], v[56:59]
	v_mfma_f32_16x16x32_bf16 v[44:47], v[188:191], v[204:207], v[44:47]
	v_mfma_f32_16x16x32_bf16 v[40:43], v[196:199], v[204:207], v[40:43]
	v_alignbit_b32 v248, v244, v248, 8
	v_mfma_f32_16x16x32_bf16 v[28:31], v[188:191], v[212:215], v[28:31]
	v_mfma_f32_16x16x32_bf16 v[24:27], v[196:199], v[212:215], v[24:27]
	v_mfma_f32_16x16x32_bf16 v[10:13], v[188:191], v[220:223], v[12:15]
	v_mfma_f32_16x16x32_bf16 v[6:9], v[196:199], v[220:223], v[6:9]
	v_alignbit_b32 v249, v245, v249, 8
	v_mfma_f32_16x16x32_bf16 v[60:63], v[192:195], v[168:171], v[60:63]
	v_mfma_f32_16x16x32_bf16 v[56:59], v[200:203], v[168:171], v[56:59]
	v_mfma_f32_16x16x32_bf16 v[44:47], v[192:195], v[208:211], v[44:47]
	v_mfma_f32_16x16x32_bf16 v[40:43], v[200:203], v[208:211], v[40:43]
	v_alignbit_b32 v255, v246, v255, 8
	v_mfma_f32_16x16x32_bf16 v[28:31], v[192:195], v[216:219], v[28:31]
	v_mfma_f32_16x16x32_bf16 v[24:27], v[200:203], v[216:219], v[24:27]
	v_mfma_f32_16x16x32_bf16 v[12:15], v[192:195], v[224:227], v[10:13]
	v_mfma_f32_16x16x32_bf16 v[8:11], v[200:203], v[224:227], v[6:9]
	v_alignbit_b32 v149, v247, v149, 8
	s_setprio 0
	s_barrier
	s_add_u32 s26, s26, 0x100
	s_addc_u32 s27, s27, 0
	s_add_u32 s69, s69, 0x100
	s_addc_u32 s70, s70, 0
	s_cmp_ge_i32 s8, s63
	s_cbranch_scc0 .LBB0_1018

.LBB0_1050:
	s_bitcmp1_b32 s32, 31
	s_cbranch_scc0 .Lg_tail
	s_sub_u32 s75, s84, 4
	s_bfe_u32 s75, s75, 0x20002
	s_lshl_b32 s75, s75, 2
	s_add_u32 s76, s98, s75
	s_addc_u32 s77, s99, 0
	v_mbcnt_lo_u32_b32 v244, -1, 0
	v_mbcnt_hi_u32_b32 v244, -1, v244
	v_and_b32_e32 v245, 7, v244
	v_lshrrev_b32_e32 v244, 3, v244
	v_lshlrev_b32_e32 v244, 4, v244
	v_lshl_add_u32 v244, v245, 14, v244
	global_store_dword v244, v248, s[76:77]
	s_add_u32 s76, s76, 0x1000
	s_addc_u32 s77, s77, 0
	global_store_dword v244, v249, s[76:77]
	s_add_u32 s76, s76, 0x1000
	s_addc_u32 s77, s77, 0
	global_store_dword v244, v255, s[76:77]
	s_add_u32 s76, s76, 0x1000
	s_addc_u32 s77, s77, 0
	global_store_dword v244, v149, s[76:77]
	s_bitset0_b32 s32, 31

.Lg_ld_t:
	global_load_dwordx4 v[244:247], v137, s[100:101] nt
	s_add_u32 s100, s100, 0xac00
	s_addc_u32 s101, s101, 0
	s_add_u32 s84, s84, 1
	s_waitcnt vmcnt(0)
	v_fmaak_f32 v244, v244, v139, 0x4b400000
	v_fmaak_f32 v245, v245, v141, 0x4b400000
	v_fmaak_f32 v246, v246, v143, 0x4b400000
	v_fmaak_f32 v247, v247, v147, 0x4b400000
	v_alignbit_b32 v248, v244, v248, 8
	v_alignbit_b32 v249, v245, v249, 8
	v_alignbit_b32 v255, v246, v255, 8
	v_alignbit_b32 v149, v247, v149, 8
	s_and_b32 s75, s84, 3
	s_cbranch_scc1 .Lg_tail
	s_sub_u32 s75, s84, 4
	s_bfe_u32 s75, s75, 0x20002
	s_lshl_b32 s75, s75, 2
	s_add_u32 s76, s98, s75
	s_addc_u32 s77, s99, 0
	v_mbcnt_lo_u32_b32 v244, -1, 0
	v_mbcnt_hi_u32_b32 v244, -1, v244
	v_and_b32_e32 v245, 7, v244
	v_lshrrev_b32_e32 v244, 3, v244
	v_lshlrev_b32_e32 v244, 4, v244
	v_lshl_add_u32 v244, v245, 14, v244
	global_store_dword v244, v248, s[76:77]
	s_add_u32 s76, s76, 0x1000
	s_addc_u32 s77, s77, 0
	global_store_dword v244, v249, s[76:77]
	s_add_u32 s76, s76, 0x1000
	s_addc_u32 s77, s77, 0
	global_store_dword v244, v255, s[76:77]
	s_add_u32 s76, s76, 0x1000
	s_addc_u32 s77, s77, 0
	global_store_dword v244, v149, s[76:77]
	s_branch .Lg_tail

.LBB0_1147:
	s_add_u32 s86, s86, 0x1d90
	s_load_dwordx2 s[14:15], s[0:1], 0x78
	s_waitcnt lgkmcnt(0)
	s_load_dwordx2 s[16:17], s[0:1], 0x80
	s_waitcnt lgkmcnt(0)
	s_cmpk_gt_i32 s86, 0x55ff
	s_cbranch_scc1 .LBB0_1150
	v_lshlrev_b32_e32 v1, 2, v128
	v_and_b32_e32 v2, 28, v1
	v_lshlrev_b32_e32 v0, 1, v128
	v_mov_b32_e32 v5, 0
	v_lshlrev_b32_e32 v4, 2, v2
	v_and_b32_e32 v0, -16, v0
	v_lshl_add_u64 v[6:7], s[96:97], 0, v[4:5]
	s_mov_b64 s[6:7], 0x80000
	v_lshl_add_u64 v[6:7], v[6:7], 0, s[6:7]
	v_ashrrev_i32_e32 v1, 31, v0
	s_lshl_b32 s3, s86, 5
	s_lshl_b32 s22, s94, 5
	s_lshl_b32 s23, s86, 4
	s_lshl_b32 s24, s94, 4
	s_mov_b32 s21, 0
	s_mov_b32 s25, 0xac00
	v_lshlrev_b32_e32 v4, 2, v2
	s_mov_b32 s26, 0xa000
	s_mov_b32 s27, 0x15000
	s_mov_b32 s28, 0x20000
	s_mov_b32 s29, 0x2b000
	s_mov_b32 s30, 0x35000
	s_mov_b32 s31, 0x40000
	s_mov_b32 s33, 0x4b000
	s_mov_b32 s34, 0x56000
	s_mov_b32 s35, 0x60000
	s_mov_b32 s36, 0x6b000
	s_mov_b32 s37, 0x76000
	s_mov_b32 s38, 0x81000
	s_mov_b32 s39, 0x8b000
	s_mov_b32 s40, 0x96000
	s_mov_b32 s41, 0xa1000
	s_mov_b32 s42, 0x42fe0000
	s_movk_i32 s43, 0xff81
	v_mov_b32_e32 v3, 0x7f
	s_mov_b32 s44, 0x40c0c00
	s_movk_i32 s45, 0x2000
	s_mov_b32 s46, s86

.LBB0_1150:
	s_sub_u32 s86, s86, 0x1d90
	s_waitcnt vmcnt(0)
	s_barrier
	s_mov_b64 s[6:7], exec
	v_readlane_b32 s8, v254, 8
	v_readlane_b32 s9, v254, 9
	s_and_b64 s[8:9], s[6:7], s[8:9]
	s_mov_b64 exec, s[8:9]
	s_cbranch_execz .LBB0_1202
	s_add_i32 s3, 0, 0x20160
	v_mov_b32_e32 v0, s3
	s_waitcnt vmcnt(0) expcnt(0) lgkmcnt(0)
	ds_read_b32 v2, v0
	s_add_i32 s3, 0, 0x20164
	v_mov_b32_e32 v0, s3
	ds_read_b32 v0, v0
	s_waitcnt lgkmcnt(1)
	v_cmp_ne_u32_e32 vcc, 0, v2
	s_cbranch_vccnz .LBB0_1166
	v_readlane_b32 s8, v254, 0
	v_readlane_b32 s9, v254, 1
	s_load_dwordx2 s[14:15], s[8:9], 0x4
	s_load_dword s3, s[0:1], 0xb0
	s_add_u32 s8, s96, 0x4200
	s_addc_u32 s9, s97, 0
	s_add_u32 s10, s96, 0x4400
	s_addc_u32 s11, s97, 0
	s_waitcnt lgkmcnt(0)
	s_mul_i32 s3, s14, s3
	s_add_u32 s14, s96, 0x4500
	s_mul_i32 s3, s3, s15
	s_addc_u32 s15, s97, 0
	s_add_u32 s16, s96, 0x4600
	s_addc_u32 s17, s97, 0
	s_add_u32 s20, s96, 0x4700
	s_addc_u32 s21, s97, 0
	s_add_u32 s22, s96, 0x4800
	s_addc_u32 s23, s97, 0
	s_add_u32 s24, s96, 0x4900
	s_addc_u32 s25, s97, 0
	s_add_u32 s26, s96, 0x4a00
	s_addc_u32 s27, s97, 0
	s_add_u32 s28, s96, 0x4b00
	s_addc_u32 s29, s97, 0
	s_add_u32 s30, s96, 0x4c00
	s_addc_u32 s31, s97, 0
	s_add_u32 s34, s96, 0x4d00
	s_addc_u32 s35, s97, 0
	s_add_u32 s36, s96, 0x4e00
	s_addc_u32 s37, s97, 0
	s_add_u32 s38, s96, 0x4f00
	s_addc_u32 s39, s97, 0
	s_add_u32 s40, s96, 0x5000
	s_addc_u32 s41, s97, 0
	s_add_u32 s42, s96, 0x5100
	s_addc_u32 s43, s97, 0
	s_add_u32 s44, s96, 0x5200
	s_addc_u32 s45, s97, 0
	s_add_u32 s46, s96, 0x5300
	s_addc_u32 s47, s97, 0
	s_mov_b32 s33, 1
	v_mov_b32_e32 v16, 0
	s_branch .LBB0_1154
